# alternate K-traversal start (0 / K/2 with wrap) per unit in QKV and FFN-up GEMM loops to reuse L2-resident tail of previous round
# baseline (speedup 1.0000x reference)
; __device__ __forceinline__ bool tile_of(long L, int nM, int nN, int& pm, int& pn) {
;     const int nwg = nM * nN; if (L >= nwg) return false;
;     int wgid = (int)L; { const int q = nwg / NXCD, r = nwg % NXCD, xcd = wgid % NXCD, off = wgid / NXCD; wgid = (xcd < r ? xcd * (q + 1) : r * (q + 1) + (xcd - r) * q) + off; }
;     const int nig = WGM * nN, gid = wgid / nig, fm = gid * WGM, gsz = (nM - fm) < WGM ? (nM - fm) : WGM;
;     pm = fm + ((wgid % nig) % gsz); pn = (wgid % nig) / gsz; return true;
; }
;     __device__ __forceinline__ bool next(int i, Unit& u) const {
;         int pm, pj; if (!tile_of((long)i * G + c, nM, 12, pm, pj)) return false;
;         const int pn = (pj % 3) * 4 + pj / 3;
;         u.a = A + (size_t)pm * BM * D * 2; u.b = Bt + (size_t)pn * BM * D * 2; u.row0 = pm * BM; u.col0 = pn * BM; u.vlo = 0; u.vhi = 0x7fffffff; u.aux = pn; return true;
;     }
.LBB0_163:
	s_add_i32 s57, s57, 1
	s_mul_i32 s6, s57, s64
	s_mul_hi_u32 s7, s57, s43
	s_add_i32 s7, s7, s6
	s_mul_i32 s6, s57, s43
	s_add_u32 s46, s6, s42
	s_addc_u32 s47, s7, s65
	v_cmp_gt_i64_e32 vcc, s[46:47], v[142:143]
	v_cmp_lt_i64_e64 s[6:7], s[46:47], v[140:141]
	s_cbranch_vccnz .LBB0_165
	s_ashr_i32 s34, s46, 31
	s_lshr_b32 s34, s34, 29
	s_add_i32 s34, s46, s34
	s_ashr_i32 s35, s34, 3
	s_and_b32 s34, s34, -8
	s_sub_i32 s34, s46, s34
	s_cmp_lt_i32 s34, 0
	s_cselect_b32 s36, s66, 0x18c
	s_mul_i32 s34, s36, s34
	s_add_i32 s34, s34, s35
	s_mul_hi_i32 s35, s34, 0x2aaaaaab
	s_lshr_b32 s36, s35, 31
	s_ashr_i32 s35, s35, 4
	s_add_i32 s35, s35, s36
	s_lshl_b32 s36, s35, 3
	s_sub_i32 s37, 0x108, s36
	s_min_i32 s37, s37, 8
	s_abs_i32 s38, s37
	v_cvt_f32_u32_e32 v0, s38
	s_sub_i32 s46, 0, s38
	s_mulk_i32 s35, 0x60
	s_sub_i32 s34, s34, s35
	v_rcp_iflag_f32_e32 v0, v0
	s_abs_i32 s35, s34
	s_xor_b32 s39, s34, s37
	s_ashr_i32 s39, s39, 31
	v_mul_f32_e32 v0, 0x4f7ffffe, v0
	v_cvt_u32_f32_e32 v0, v0
	s_nop 0
	v_readfirstlane_b32 s47, v0
	s_mul_i32 s46, s46, s47
	s_mul_hi_u32 s46, s47, s46
	s_add_i32 s47, s47, s46
	s_mul_hi_u32 s46, s35, s47
	s_mul_i32 s47, s46, s38
	s_sub_i32 s35, s35, s47
	s_add_i32 s71, s46, 1
	s_sub_i32 s47, s35, s38
	s_cmp_ge_u32 s35, s38
	s_cselect_b32 s46, s71, s46
	s_cselect_b32 s35, s47, s35
	s_add_i32 s47, s46, 1
	s_cmp_ge_u32 s35, s38
	s_cselect_b32 s35, s47, s46
	s_xor_b32 s35, s35, s39
	s_sub_i32 s35, s35, s39
	s_mul_i32 s37, s35, s37
	s_sub_i32 s34, s34, s37
	s_add_i32 s46, s34, s36
	s_bfe_i32 s34, s35, 0x80000
	s_mulk_i32 s34, 0x56
	s_bfe_u32 s36, s34, 0x1000f
	s_bfe_u32 s34, s34, 0x80008
	s_add_i32 s34, s34, s36
	s_mul_i32 s36, s34, 3
	s_sub_i32 s35, s35, s36
	s_sext_i32_i8 s35, s35
	s_lshl_b32 s35, s35, 2
	s_sext_i32_i8 s34, s34
	s_ashr_i32 s47, s46, 31
	s_add_i32 s34, s35, s34
	s_lshl_b64 s[36:37], s[46:47], 19
	s_add_u32 s36, s48, s36
	s_addc_u32 s37, s49, s37
	s_ashr_i32 s35, s34, 31
	s_lshl_b64 s[38:39], s[34:35], 19
	s_add_u32 s38, s50, s38
	s_addc_u32 s39, s51, s39
	s_bitcmp1_b32 s57, 0
	s_cselect_b32 s78, 0x400, 0
	s_add_u32 s36, s36, s78
	s_addc_u32 s37, s37, 0
	s_add_u32 s38, s38, s78
	s_addc_u32 s39, s39, 0
	s_lshl_b32 s35, s46, 8
.LBB0_165:
	s_bitcmp0_b32 s57, 0
	s_cselect_b32 s77, 0x800, 0
	s_add_u32 s71, s44, 0x100
	s_addc_u32 s72, s45, 0
	s_add_u32 s4, s4, 0x40080
	v_mov_b32_e32 v0, 0
	s_addc_u32 s5, s5, 0
	s_mov_b32 s73, -2
	v_mov_b32_e32 v1, v0
	v_mov_b32_e32 v2, v0
	v_mov_b32_e32 v3, v0
	v_mov_b32_e32 v4, v0
	v_mov_b32_e32 v5, v0
	v_mov_b32_e32 v6, v0
	v_mov_b32_e32 v7, v0
	v_mov_b32_e32 v16, v0
	v_mov_b32_e32 v17, v0
	v_mov_b32_e32 v18, v0
	v_mov_b32_e32 v19, v0
	v_mov_b32_e32 v20, v0
	v_mov_b32_e32 v21, v0
	v_mov_b32_e32 v22, v0
	v_mov_b32_e32 v23, v0
	v_mov_b32_e32 v32, v0
	v_mov_b32_e32 v33, v0
	v_mov_b32_e32 v34, v0
	v_mov_b32_e32 v35, v0
	v_mov_b32_e32 v36, v0
	v_mov_b32_e32 v37, v0
	v_mov_b32_e32 v38, v0
	v_mov_b32_e32 v39, v0
	v_mov_b32_e32 v48, v0
	v_mov_b32_e32 v49, v0
	v_mov_b32_e32 v50, v0
	v_mov_b32_e32 v51, v0
	v_mov_b32_e32 v52, v0
	v_mov_b32_e32 v53, v0
	v_mov_b32_e32 v54, v0
	v_mov_b32_e32 v55, v0
	v_mov_b32_e32 v8, v0
	v_mov_b32_e32 v9, v0
	v_mov_b32_e32 v10, v0
	v_mov_b32_e32 v11, v0
	v_mov_b32_e32 v12, v0
	v_mov_b32_e32 v13, v0
	v_mov_b32_e32 v14, v0
	v_mov_b32_e32 v15, v0
	v_mov_b32_e32 v24, v0
	v_mov_b32_e32 v25, v0
	v_mov_b32_e32 v26, v0
	v_mov_b32_e32 v27, v0
	v_mov_b32_e32 v28, v0
	v_mov_b32_e32 v29, v0
	v_mov_b32_e32 v30, v0
	v_mov_b32_e32 v31, v0
	v_mov_b32_e32 v40, v0
	v_mov_b32_e32 v41, v0
	v_mov_b32_e32 v42, v0
	v_mov_b32_e32 v43, v0
	v_mov_b32_e32 v44, v0
	v_mov_b32_e32 v45, v0
	v_mov_b32_e32 v46, v0
	v_mov_b32_e32 v47, v0
	v_mov_b32_e32 v56, v0
	v_mov_b32_e32 v57, v0
	v_mov_b32_e32 v58, v0
	v_mov_b32_e32 v59, v0
	v_mov_b32_e32 v60, v0
	v_mov_b32_e32 v61, v0
	v_mov_b32_e32 v62, v0
	v_mov_b32_e32 v63, v0
	v_mov_b32_e32 v64, v0
	v_mov_b32_e32 v65, v0
	v_mov_b32_e32 v66, v0
	v_mov_b32_e32 v67, v0
	v_mov_b32_e32 v68, v0
	v_mov_b32_e32 v69, v0
	v_mov_b32_e32 v70, v0
	v_mov_b32_e32 v71, v0
	v_mov_b32_e32 v80, v0
	v_mov_b32_e32 v81, v0
	v_mov_b32_e32 v82, v0
	v_mov_b32_e32 v83, v0
	v_mov_b32_e32 v84, v0
	v_mov_b32_e32 v85, v0
	v_mov_b32_e32 v86, v0
	v_mov_b32_e32 v87, v0
	v_mov_b32_e32 v96, v0
	v_mov_b32_e32 v97, v0
	v_mov_b32_e32 v98, v0
	v_mov_b32_e32 v99, v0
	v_mov_b32_e32 v100, v0
	v_mov_b32_e32 v101, v0
	v_mov_b32_e32 v102, v0
	v_mov_b32_e32 v103, v0
	v_mov_b32_e32 v112, v0
	v_mov_b32_e32 v113, v0
	v_mov_b32_e32 v114, v0
	v_mov_b32_e32 v115, v0
	v_mov_b32_e32 v116, v0
	v_mov_b32_e32 v117, v0
	v_mov_b32_e32 v118, v0
	v_mov_b32_e32 v119, v0
	v_mov_b32_e32 v72, v0
	v_mov_b32_e32 v73, v0
	v_mov_b32_e32 v74, v0
	v_mov_b32_e32 v75, v0
	v_mov_b32_e32 v76, v0
	v_mov_b32_e32 v77, v0
	v_mov_b32_e32 v78, v0
	v_mov_b32_e32 v79, v0
	v_mov_b32_e32 v88, v0
	v_mov_b32_e32 v89, v0
	v_mov_b32_e32 v90, v0
	v_mov_b32_e32 v91, v0
	v_mov_b32_e32 v92, v0
	v_mov_b32_e32 v93, v0
	v_mov_b32_e32 v94, v0
	v_mov_b32_e32 v95, v0
	v_mov_b32_e32 v104, v0
	v_mov_b32_e32 v105, v0
	v_mov_b32_e32 v106, v0
	v_mov_b32_e32 v107, v0
	v_mov_b32_e32 v108, v0
	v_mov_b32_e32 v109, v0
	v_mov_b32_e32 v110, v0
	v_mov_b32_e32 v111, v0
	v_mov_b32_e32 v120, v0
	v_mov_b32_e32 v121, v0
	v_mov_b32_e32 v122, v0
	v_mov_b32_e32 v123, v0
	v_mov_b32_e32 v124, v0
	v_mov_b32_e32 v125, v0
	v_mov_b32_e32 v126, v0
	v_mov_b32_e32 v127, v0
; #define PG8_STAGE(bufoff, gbase, voff) do { _Pragma("unroll") for (int _i = 0; _i < 2; ++_i) \
;         __builtin_amdgcn_global_load_lds((const unsigned*)((const char*)(gbase) + (voff)[_i]), (LAS unsigned*)(lds + (bufoff) + ldsw + _i * 8192), 16, 0, 0); } while (0)
; #define PG8_LDA(dst, b, h) do { _Pragma("unroll") for (int m = 0; m < 4; ++m) _Pragma("unroll") for (int k = 0; k < 2; ++k) dst[m][k] = *(const LAS bf16x8*)(lds + PG8_SA(b, h) + aoff + m * 2048 + k * 1024); } while (0)
; #define PG8_LDB(dst, b, h) do { _Pragma("unroll") for (int n = 0; n < 2; ++n) _Pragma("unroll") for (int k = 0; k < 2; ++k) dst[n][k] = *(const LAS bf16x8*)(lds + PG8_SB(b, h) + boff + n * 2048 + k * 1024); } while (0)
; #define PG8_MMA(ai, bj, At, Bt) do { __builtin_amdgcn_s_setprio(1); _Pragma("unroll") for (int m = 0; m < 4; ++m) _Pragma("unroll") for (int n = 0; n < 2; ++n) _Pragma("unroll") for (int k = 0; k < 2; ++k) \
;         acc[ai][bj][m][n] = __builtin_amdgcn_mfma_f32_16x16x32_bf16(Bt[n][k], At[m][k], acc[ai][bj][m][n], 0, 0, 0); __builtin_amdgcn_s_setprio(0); } while (0)
; #define PG8_WAIT_V(n) asm volatile("s_waitcnt vmcnt(" #n ")" ::: "memory")
; #define PG8_WAIT_L(n) asm volatile("s_waitcnt lgkmcnt(" #n ")" ::: "memory")
; #define PG8_BAR __builtin_amdgcn_s_barrier()
; #define PG8_SCHED __builtin_amdgcn_sched_barrier(0)
; template <class Epi, class Sched>
; __device__ __forceinline__ void gemm_phase(LAS unsigned char* lds, const GemmP g, const Sched& S, const Epi& E, int tid) {
;     ...
;         for (int t = 0; t < nt; t += 2) {
;             const bool last = (t == nt - 2);
;             const char* a1 = cA + (size_t)(t + 1) * kstep;
;             const char* a2 = last ? nA : cA + (size_t)(t + 2) * kstep; const char* b2 = last ? nB : cB + (size_t)(t + 2) * kstep;
;             const char* a3 = a2 + kstep; const char* b3 = b2 + kstep;
;             PG8_LDB(B0, 0, 0); PG8_LDB(B1, 0, 1); PG8_SCHED; PG8_LDA(At, 0, 0); PG8_STAGE(PG8_SA(1, 1), a1 + hstepA, voffA);
;             PG8_WAIT_V(8); PG8_WAIT_L(0); PG8_BAR; PG8_MMA(0, 0, At, B0); PG8_MMA(0, 1, At, B1); PG8_BAR; PG8_SCHED;
;             PG8_LDA(At, 0, 1); PG8_STAGE(PG8_SB(0, 0), b2, voffB); PG8_STAGE(PG8_SB(0, 1), b2 + hstepB, voffB); PG8_STAGE(PG8_SA(0, 0), a2, voffA);
;             PG8_WAIT_V(8); PG8_WAIT_L(0); PG8_BAR; PG8_MMA(1, 0, At, B0); PG8_MMA(1, 1, At, B1); PG8_BAR; PG8_SCHED;
.LBB0_166:
	ds_read_b128 v[144:147], v157
	ds_read_b128 v[148:151], v157 offset:1024
	ds_read_b128 v[152:155], v157 offset:2048
	ds_read_b128 v[162:165], v157 offset:3072
	ds_read_b128 v[166:169], v158
	ds_read_b128 v[170:173], v158 offset:1024
	ds_read_b128 v[174:177], v158 offset:2048
	ds_read_b128 v[178:181], v158 offset:3072
	s_add_u32 s44, s4, 0xfffc0080
	s_addc_u32 s45, s5, -1
	s_cmp_eq_u32 s73, 12
	s_cselect_b32 s47, s37, s45
	s_cselect_b32 s46, s36, s44
	s_cselect_b32 s45, s39, s72
	s_cselect_b32 s44, s38, s71
	s_cmp_eq_u32 s73, 4
	s_cselect_b32 s78, s77, 0
	s_sub_u32 s44, s44, s78
	s_subb_u32 s45, s45, 0
	s_sub_u32 s46, s46, s78
	s_subb_u32 s47, s47, 0
	v_lshl_add_u64 v[214:215], s[4:5], 0, v[138:139]
	s_add_i32 m0, s53, 0xc000
	ds_read_b128 v[182:185], v159
	ds_read_b128 v[186:189], v159 offset:1024
	ds_read_b128 v[190:193], v159 offset:2048
	ds_read_b128 v[194:197], v159 offset:3072
	ds_read_b128 v[198:201], v159 offset:4096
	ds_read_b128 v[202:205], v159 offset:5120
	ds_read_b128 v[206:209], v159 offset:6144
	ds_read_b128 v[210:213], v159 offset:7168
	global_load_lds_dwordx4 v[214:215], off
	v_lshl_add_u64 v[214:215], s[4:5], 0, v[136:137]
	s_add_i32 m0, s53, 0xe000
	s_nop 0
	global_load_lds_dwordx4 v[214:215], off
	s_cmp_eq_u32 s73, -2
	s_cbranch_scc1 .Lfirstit_1
	s_waitcnt vmcnt(8)
.Lfirstit_1:
	s_waitcnt lgkmcnt(0)
	s_barrier
	s_setprio 1
	s_waitcnt lgkmcnt(0)
	v_mfma_f32_16x16x32_bf16 v[124:127], v[144:147], v[182:185], v[124:127]
	v_mfma_f32_16x16x32_bf16 v[120:123], v[152:155], v[182:185], v[120:123]
	v_mfma_f32_16x16x32_bf16 v[108:111], v[144:147], v[190:193], v[108:111]
	v_mfma_f32_16x16x32_bf16 v[104:107], v[152:155], v[190:193], v[104:107]
	v_mfma_f32_16x16x32_bf16 v[92:95], v[144:147], v[198:201], v[92:95]
	v_mfma_f32_16x16x32_bf16 v[88:91], v[152:155], v[198:201], v[88:91]
	v_mfma_f32_16x16x32_bf16 v[76:79], v[144:147], v[206:209], v[76:79]
	v_mfma_f32_16x16x32_bf16 v[72:75], v[152:155], v[206:209], v[72:75]
	v_mfma_f32_16x16x32_bf16 v[124:127], v[148:151], v[186:189], v[124:127]
	v_mfma_f32_16x16x32_bf16 v[120:123], v[162:165], v[186:189], v[120:123]
	v_mfma_f32_16x16x32_bf16 v[108:111], v[148:151], v[194:197], v[108:111]
	v_mfma_f32_16x16x32_bf16 v[104:107], v[162:165], v[194:197], v[104:107]
	v_mfma_f32_16x16x32_bf16 v[92:95], v[148:151], v[202:205], v[92:95]
	v_mfma_f32_16x16x32_bf16 v[88:91], v[162:165], v[202:205], v[88:91]
	v_mfma_f32_16x16x32_bf16 v[76:79], v[148:151], v[210:213], v[76:79]
	v_mfma_f32_16x16x32_bf16 v[72:75], v[162:165], v[210:213], v[72:75]
	s_setprio 0
	s_setprio 1
	v_mfma_f32_16x16x32_bf16 v[116:119], v[166:169], v[182:185], v[116:119]
	v_mfma_f32_16x16x32_bf16 v[112:115], v[174:177], v[182:185], v[112:115]
	v_mfma_f32_16x16x32_bf16 v[100:103], v[166:169], v[190:193], v[100:103]
	v_mfma_f32_16x16x32_bf16 v[96:99], v[174:177], v[190:193], v[96:99]
	v_mfma_f32_16x16x32_bf16 v[84:87], v[166:169], v[198:201], v[84:87]
	v_mfma_f32_16x16x32_bf16 v[80:83], v[174:177], v[198:201], v[80:83]
	v_mfma_f32_16x16x32_bf16 v[68:71], v[166:169], v[206:209], v[68:71]
	v_mfma_f32_16x16x32_bf16 v[64:67], v[174:177], v[206:209], v[64:67]
	v_mfma_f32_16x16x32_bf16 v[116:119], v[170:173], v[186:189], v[116:119]
	v_mfma_f32_16x16x32_bf16 v[112:115], v[178:181], v[186:189], v[112:115]
	v_mfma_f32_16x16x32_bf16 v[100:103], v[170:173], v[194:197], v[100:103]
	v_mfma_f32_16x16x32_bf16 v[96:99], v[178:181], v[194:197], v[96:99]
	v_mfma_f32_16x16x32_bf16 v[84:87], v[170:173], v[202:205], v[84:87]
	v_mfma_f32_16x16x32_bf16 v[80:83], v[178:181], v[202:205], v[80:83]
	v_mfma_f32_16x16x32_bf16 v[68:71], v[170:173], v[210:213], v[68:71]
	v_mfma_f32_16x16x32_bf16 v[64:67], v[178:181], v[210:213], v[64:67]
	s_setprio 0
	s_barrier
	s_add_i32 s74, s67, s52
	v_lshl_add_u64 v[214:215], s[44:45], 0, v[130:131]
	s_mov_b32 m0, s74
	ds_read_b128 v[182:185], v159 offset:16384
	ds_read_b128 v[186:189], v159 offset:17408
	ds_read_b128 v[190:193], v159 offset:18432
	ds_read_b128 v[194:197], v159 offset:19456
	ds_read_b128 v[198:201], v159 offset:20480
	ds_read_b128 v[202:205], v159 offset:21504
	ds_read_b128 v[206:209], v159 offset:22528
	ds_read_b128 v[210:213], v159 offset:23552
	global_load_lds_dwordx4 v[214:215], off
	s_add_i32 m0, s74, 0x2000
	s_add_u32 s74, s44, 0x40000
	v_lshl_add_u64 v[216:217], s[44:45], 0, v[134:135]
	s_addc_u32 s75, s45, 0
	s_add_i32 s76, s68, s52
	global_load_lds_dwordx4 v[216:217], off
	v_lshl_add_u64 v[218:219], s[74:75], 0, v[130:131]
	s_mov_b32 m0, s76
	v_lshl_add_u64 v[220:221], s[46:47], 0, v[132:133]
	global_load_lds_dwordx4 v[218:219], off
	v_lshl_add_u64 v[218:219], s[74:75], 0, v[134:135]
	s_add_i32 m0, s76, 0x2000
	s_nop 0
	global_load_lds_dwordx4 v[218:219], off
	v_lshl_add_u64 v[218:219], s[46:47], 0, v[128:129]
	s_mov_b32 m0, s53
	s_nop 0
	global_load_lds_dwordx4 v[218:219], off
	s_mov_b32 m0, s54
	s_nop 0
	global_load_lds_dwordx4 v[220:221], off
	s_waitcnt vmcnt(8)
	s_waitcnt lgkmcnt(0)
	s_barrier
; #define PG8_STAGE(bufoff, gbase, voff) do { _Pragma("unroll") for (int _i = 0; _i < 2; ++_i) \
;         __builtin_amdgcn_global_load_lds((const unsigned*)((const char*)(gbase) + (voff)[_i]), (LAS unsigned*)(lds + (bufoff) + ldsw + _i * 8192), 16, 0, 0); } while (0)
; #define PG8_LDA(dst, b, h) do { _Pragma("unroll") for (int m = 0; m < 4; ++m) _Pragma("unroll") for (int k = 0; k < 2; ++k) dst[m][k] = *(const LAS bf16x8*)(lds + PG8_SA(b, h) + aoff + m * 2048 + k * 1024); } while (0)
; #define PG8_LDB(dst, b, h) do { _Pragma("unroll") for (int n = 0; n < 2; ++n) _Pragma("unroll") for (int k = 0; k < 2; ++k) dst[n][k] = *(const LAS bf16x8*)(lds + PG8_SB(b, h) + boff + n * 2048 + k * 1024); } while (0)
; #define PG8_MMA(ai, bj, At, Bt) do { __builtin_amdgcn_s_setprio(1); _Pragma("unroll") for (int m = 0; m < 4; ++m) _Pragma("unroll") for (int n = 0; n < 2; ++n) _Pragma("unroll") for (int k = 0; k < 2; ++k) \
;         acc[ai][bj][m][n] = __builtin_amdgcn_mfma_f32_16x16x32_bf16(Bt[n][k], At[m][k], acc[ai][bj][m][n], 0, 0, 0); __builtin_amdgcn_s_setprio(0); } while (0)
; #define PG8_WAIT_V(n) asm volatile("s_waitcnt vmcnt(" #n ")" ::: "memory")
; #define PG8_WAIT_L(n) asm volatile("s_waitcnt lgkmcnt(" #n ")" ::: "memory")
; #define PG8_BAR __builtin_amdgcn_s_barrier()
; #define PG8_SCHED __builtin_amdgcn_sched_barrier(0)
; template <class Epi, class Sched>
; __device__ __forceinline__ void gemm_phase(LAS unsigned char* lds, const GemmP g, const Sched& S, const Epi& E, int tid) {
;     ...
;             PG8_WAIT_V(8); PG8_WAIT_L(0); PG8_BAR; PG8_MMA(1, 0, At, B0); PG8_MMA(1, 1, At, B1); PG8_BAR; PG8_SCHED;
;             PG8_LDB(B0, 1, 0); PG8_LDB(B1, 1, 1); PG8_SCHED; PG8_LDA(At, 1, 0); PG8_STAGE(PG8_SA(0, 1), a2 + hstepA, voffA);
;             PG8_WAIT_V(8); PG8_WAIT_L(0); PG8_BAR; PG8_MMA(0, 0, At, B0); PG8_MMA(0, 1, At, B1); PG8_BAR; PG8_SCHED;
	s_setprio 1
	s_waitcnt lgkmcnt(0)
	v_mfma_f32_16x16x32_bf16 v[60:63], v[144:147], v[182:185], v[60:63]
	v_mfma_f32_16x16x32_bf16 v[56:59], v[152:155], v[182:185], v[56:59]
	v_mfma_f32_16x16x32_bf16 v[44:47], v[144:147], v[190:193], v[44:47]
	v_mfma_f32_16x16x32_bf16 v[40:43], v[152:155], v[190:193], v[40:43]
	v_mfma_f32_16x16x32_bf16 v[28:31], v[144:147], v[198:201], v[28:31]
	v_mfma_f32_16x16x32_bf16 v[24:27], v[152:155], v[198:201], v[24:27]
	v_mfma_f32_16x16x32_bf16 v[12:15], v[144:147], v[206:209], v[12:15]
	v_mfma_f32_16x16x32_bf16 v[8:11], v[152:155], v[206:209], v[8:11]
	v_mfma_f32_16x16x32_bf16 v[60:63], v[148:151], v[186:189], v[60:63]
	v_mfma_f32_16x16x32_bf16 v[56:59], v[162:165], v[186:189], v[56:59]
	v_mfma_f32_16x16x32_bf16 v[44:47], v[148:151], v[194:197], v[44:47]
	v_mfma_f32_16x16x32_bf16 v[40:43], v[162:165], v[194:197], v[40:43]
	v_mfma_f32_16x16x32_bf16 v[28:31], v[148:151], v[202:205], v[28:31]
	v_mfma_f32_16x16x32_bf16 v[24:27], v[162:165], v[202:205], v[24:27]
	v_mfma_f32_16x16x32_bf16 v[12:15], v[148:151], v[210:213], v[12:15]
	v_mfma_f32_16x16x32_bf16 v[8:11], v[162:165], v[210:213], v[8:11]
	s_setprio 0
	s_setprio 1
	v_mfma_f32_16x16x32_bf16 v[52:55], v[166:169], v[182:185], v[52:55]
	v_mfma_f32_16x16x32_bf16 v[48:51], v[174:177], v[182:185], v[48:51]
	v_mfma_f32_16x16x32_bf16 v[36:39], v[166:169], v[190:193], v[36:39]
	v_mfma_f32_16x16x32_bf16 v[32:35], v[174:177], v[190:193], v[32:35]
	v_mfma_f32_16x16x32_bf16 v[20:23], v[166:169], v[198:201], v[20:23]
	v_mfma_f32_16x16x32_bf16 v[16:19], v[174:177], v[198:201], v[16:19]
	v_mfma_f32_16x16x32_bf16 v[4:7], v[166:169], v[206:209], v[4:7]
	v_mfma_f32_16x16x32_bf16 v[0:3], v[174:177], v[206:209], v[0:3]
	v_mfma_f32_16x16x32_bf16 v[52:55], v[170:173], v[186:189], v[52:55]
	v_mfma_f32_16x16x32_bf16 v[48:51], v[178:181], v[186:189], v[48:51]
	v_mfma_f32_16x16x32_bf16 v[36:39], v[170:173], v[194:197], v[36:39]
	v_mfma_f32_16x16x32_bf16 v[32:35], v[178:181], v[194:197], v[32:35]
	v_mfma_f32_16x16x32_bf16 v[20:23], v[170:173], v[202:205], v[20:23]
	v_mfma_f32_16x16x32_bf16 v[16:19], v[178:181], v[202:205], v[16:19]
	v_mfma_f32_16x16x32_bf16 v[4:7], v[170:173], v[210:213], v[4:7]
	v_mfma_f32_16x16x32_bf16 v[0:3], v[178:181], v[210:213], v[0:3]
	s_setprio 0
	s_barrier
	s_add_i32 s74, 0, 0x18000
	s_add_i32 s75, 0, 0x1c000
	v_add_u32_e32 v162, s74, v156
	v_add_u32_e32 v178, s75, v156
	ds_read_b128 v[144:147], v162
	ds_read_b128 v[148:151], v162 offset:1024
	ds_read_b128 v[152:155], v162 offset:2048
	ds_read_b128 v[162:165], v162 offset:3072
	ds_read_b128 v[166:169], v178
	ds_read_b128 v[170:173], v178 offset:1024
	ds_read_b128 v[174:177], v178 offset:2048
	ds_read_b128 v[178:181], v178 offset:3072
	s_add_u32 s46, s46, 0x40000
	s_addc_u32 s47, s47, 0
	s_mov_b32 m0, s55
	v_lshl_add_u64 v[222:223], s[46:47], 0, v[128:129]
	ds_read_b128 v[182:185], v159 offset:32768
	ds_read_b128 v[186:189], v159 offset:33792
	ds_read_b128 v[190:193], v159 offset:34816
	ds_read_b128 v[194:197], v159 offset:35840
	ds_read_b128 v[198:201], v159 offset:36864
	ds_read_b128 v[202:205], v159 offset:37888
	ds_read_b128 v[206:209], v159 offset:38912
	ds_read_b128 v[210:213], v159 offset:39936
	global_load_lds_dwordx4 v[222:223], off
	v_lshl_add_u64 v[222:223], s[46:47], 0, v[132:133]
	s_mov_b32 m0, s56
	s_nop 0
	global_load_lds_dwordx4 v[222:223], off
	s_waitcnt vmcnt(8)
	s_waitcnt lgkmcnt(0)
	s_barrier
	s_setprio 1
	s_waitcnt lgkmcnt(0)
	v_mfma_f32_16x16x32_bf16 v[124:127], v[144:147], v[182:185], v[124:127]
	v_mfma_f32_16x16x32_bf16 v[120:123], v[152:155], v[182:185], v[120:123]
	v_mfma_f32_16x16x32_bf16 v[108:111], v[144:147], v[190:193], v[108:111]
	v_mfma_f32_16x16x32_bf16 v[104:107], v[152:155], v[190:193], v[104:107]
	v_mfma_f32_16x16x32_bf16 v[92:95], v[144:147], v[198:201], v[92:95]
	v_mfma_f32_16x16x32_bf16 v[88:91], v[152:155], v[198:201], v[88:91]
	v_mfma_f32_16x16x32_bf16 v[76:79], v[144:147], v[206:209], v[76:79]
	v_mfma_f32_16x16x32_bf16 v[72:75], v[152:155], v[206:209], v[72:75]
	v_mfma_f32_16x16x32_bf16 v[124:127], v[148:151], v[186:189], v[124:127]
	v_mfma_f32_16x16x32_bf16 v[120:123], v[162:165], v[186:189], v[120:123]
	v_mfma_f32_16x16x32_bf16 v[108:111], v[148:151], v[194:197], v[108:111]
	v_mfma_f32_16x16x32_bf16 v[104:107], v[162:165], v[194:197], v[104:107]
	v_mfma_f32_16x16x32_bf16 v[92:95], v[148:151], v[202:205], v[92:95]
	v_mfma_f32_16x16x32_bf16 v[88:91], v[162:165], v[202:205], v[88:91]
	v_mfma_f32_16x16x32_bf16 v[76:79], v[148:151], v[210:213], v[76:79]
	v_mfma_f32_16x16x32_bf16 v[72:75], v[162:165], v[210:213], v[72:75]
	s_setprio 0
	s_setprio 1
	v_mfma_f32_16x16x32_bf16 v[116:119], v[166:169], v[182:185], v[116:119]
	v_mfma_f32_16x16x32_bf16 v[112:115], v[174:177], v[182:185], v[112:115]
	v_mfma_f32_16x16x32_bf16 v[100:103], v[166:169], v[190:193], v[100:103]
	v_mfma_f32_16x16x32_bf16 v[96:99], v[174:177], v[190:193], v[96:99]
	v_mfma_f32_16x16x32_bf16 v[84:87], v[166:169], v[198:201], v[84:87]
	v_mfma_f32_16x16x32_bf16 v[80:83], v[174:177], v[198:201], v[80:83]
	v_mfma_f32_16x16x32_bf16 v[68:71], v[166:169], v[206:209], v[68:71]
	v_mfma_f32_16x16x32_bf16 v[64:67], v[174:177], v[206:209], v[64:67]
	v_mfma_f32_16x16x32_bf16 v[116:119], v[170:173], v[186:189], v[116:119]
	v_mfma_f32_16x16x32_bf16 v[112:115], v[178:181], v[186:189], v[112:115]
	v_mfma_f32_16x16x32_bf16 v[100:103], v[170:173], v[194:197], v[100:103]
	v_mfma_f32_16x16x32_bf16 v[96:99], v[178:181], v[194:197], v[96:99]
	v_mfma_f32_16x16x32_bf16 v[84:87], v[170:173], v[202:205], v[84:87]
	v_mfma_f32_16x16x32_bf16 v[80:83], v[178:181], v[202:205], v[80:83]
	v_mfma_f32_16x16x32_bf16 v[68:71], v[170:173], v[210:213], v[68:71]
	v_mfma_f32_16x16x32_bf16 v[64:67], v[178:181], v[210:213], v[64:67]
	s_setprio 0
	s_barrier
; #define PG8_STAGE(bufoff, gbase, voff) do { _Pragma("unroll") for (int _i = 0; _i < 2; ++_i) \
;         __builtin_amdgcn_global_load_lds((const unsigned*)((const char*)(gbase) + (voff)[_i]), (LAS unsigned*)(lds + (bufoff) + ldsw + _i * 8192), 16, 0, 0); } while (0)
; #define PG8_LDA(dst, b, h) do { _Pragma("unroll") for (int m = 0; m < 4; ++m) _Pragma("unroll") for (int k = 0; k < 2; ++k) dst[m][k] = *(const LAS bf16x8*)(lds + PG8_SA(b, h) + aoff + m * 2048 + k * 1024); } while (0)
; #define PG8_MMA(ai, bj, At, Bt) do { __builtin_amdgcn_s_setprio(1); _Pragma("unroll") for (int m = 0; m < 4; ++m) _Pragma("unroll") for (int n = 0; n < 2; ++n) _Pragma("unroll") for (int k = 0; k < 2; ++k) \
;         acc[ai][bj][m][n] = __builtin_amdgcn_mfma_f32_16x16x32_bf16(Bt[n][k], At[m][k], acc[ai][bj][m][n], 0, 0, 0); __builtin_amdgcn_s_setprio(0); } while (0)
; #define PG8_WAIT_V(n) asm volatile("s_waitcnt vmcnt(" #n ")" ::: "memory")
; #define PG8_WAIT_L(n) asm volatile("s_waitcnt lgkmcnt(" #n ")" ::: "memory")
; #define PG8_BAR __builtin_amdgcn_s_barrier()
; #define PG8_SCHED __builtin_amdgcn_sched_barrier(0)
; template <class Epi, class Sched>
; __device__ __forceinline__ void gemm_phase(LAS unsigned char* lds, const GemmP g, const Sched& S, const Epi& E, int tid) {
;     ...
;         for (int t = 0; t < nt; t += 2) {
;     ...
;             PG8_LDA(At, 1, 1); PG8_STAGE(PG8_SB(1, 0), b3, voffB); PG8_STAGE(PG8_SB(1, 1), b3 + hstepB, voffB); PG8_STAGE(PG8_SA(1, 0), a3, voffA);
;             PG8_WAIT_V(8); PG8_WAIT_L(0); PG8_BAR; PG8_MMA(1, 0, At, B0); PG8_MMA(1, 1, At, B1); PG8_BAR; PG8_SCHED;
	s_add_i32 s46, s74, s52
	v_lshl_add_u64 v[214:215], v[214:215], 0, s[14:15]
	s_mov_b32 m0, s46
	ds_read_b128 v[182:185], v159 offset:49152
	ds_read_b128 v[186:189], v159 offset:50176
	ds_read_b128 v[190:193], v159 offset:51200
	ds_read_b128 v[194:197], v159 offset:52224
	ds_read_b128 v[198:201], v159 offset:53248
	ds_read_b128 v[202:205], v159 offset:54272
	ds_read_b128 v[206:209], v159 offset:55296
	ds_read_b128 v[210:213], v159 offset:56320
	global_load_lds_dwordx4 v[214:215], off
	s_add_i32 m0, s46, 0x2000
	s_add_u32 s44, s44, 0x40080
	v_lshl_add_u64 v[214:215], v[216:217], 0, s[14:15]
	s_addc_u32 s45, s45, 0
	s_add_i32 s46, s75, s52
	global_load_lds_dwordx4 v[214:215], off
	v_lshl_add_u64 v[214:215], s[44:45], 0, v[130:131]
	s_mov_b32 m0, s46
	s_nop 0
	global_load_lds_dwordx4 v[214:215], off
	v_lshl_add_u64 v[214:215], s[44:45], 0, v[134:135]
	s_add_i32 m0, s46, 0x2000
	s_nop 0
	global_load_lds_dwordx4 v[214:215], off
	v_lshl_add_u64 v[214:215], v[218:219], 0, s[14:15]
	s_mov_b32 m0, s62
	s_nop 0
	global_load_lds_dwordx4 v[214:215], off
	v_lshl_add_u64 v[214:215], v[220:221], 0, s[14:15]
	s_mov_b32 m0, s63
	s_nop 0
	global_load_lds_dwordx4 v[214:215], off
	s_waitcnt vmcnt(8)
	s_waitcnt lgkmcnt(0)
	s_barrier
	s_setprio 1
	s_waitcnt lgkmcnt(0)
	v_mfma_f32_16x16x32_bf16 v[60:63], v[144:147], v[182:185], v[60:63]
	v_mfma_f32_16x16x32_bf16 v[56:59], v[152:155], v[182:185], v[56:59]
	v_mfma_f32_16x16x32_bf16 v[44:47], v[144:147], v[190:193], v[44:47]
	v_mfma_f32_16x16x32_bf16 v[40:43], v[152:155], v[190:193], v[40:43]
	v_mfma_f32_16x16x32_bf16 v[28:31], v[144:147], v[198:201], v[28:31]
	v_mfma_f32_16x16x32_bf16 v[24:27], v[152:155], v[198:201], v[24:27]
	v_mfma_f32_16x16x32_bf16 v[12:15], v[144:147], v[206:209], v[12:15]
	v_mfma_f32_16x16x32_bf16 v[8:11], v[152:155], v[206:209], v[8:11]
	v_mfma_f32_16x16x32_bf16 v[60:63], v[148:151], v[186:189], v[60:63]
	v_mfma_f32_16x16x32_bf16 v[56:59], v[162:165], v[186:189], v[56:59]
	v_mfma_f32_16x16x32_bf16 v[44:47], v[148:151], v[194:197], v[44:47]
	v_mfma_f32_16x16x32_bf16 v[40:43], v[162:165], v[194:197], v[40:43]
	v_mfma_f32_16x16x32_bf16 v[28:31], v[148:151], v[202:205], v[28:31]
	v_mfma_f32_16x16x32_bf16 v[24:27], v[162:165], v[202:205], v[24:27]
	v_mfma_f32_16x16x32_bf16 v[12:15], v[148:151], v[210:213], v[12:15]
	v_mfma_f32_16x16x32_bf16 v[8:11], v[162:165], v[210:213], v[8:11]
	s_setprio 0
	s_setprio 1
	v_mfma_f32_16x16x32_bf16 v[52:55], v[166:169], v[182:185], v[52:55]
	v_mfma_f32_16x16x32_bf16 v[48:51], v[174:177], v[182:185], v[48:51]
	v_mfma_f32_16x16x32_bf16 v[36:39], v[166:169], v[190:193], v[36:39]
	v_mfma_f32_16x16x32_bf16 v[32:35], v[174:177], v[190:193], v[32:35]
	v_mfma_f32_16x16x32_bf16 v[20:23], v[166:169], v[198:201], v[20:23]
	v_mfma_f32_16x16x32_bf16 v[16:19], v[174:177], v[198:201], v[16:19]
	v_mfma_f32_16x16x32_bf16 v[4:7], v[166:169], v[206:209], v[4:7]
	v_mfma_f32_16x16x32_bf16 v[0:3], v[174:177], v[206:209], v[0:3]
	v_mfma_f32_16x16x32_bf16 v[52:55], v[170:173], v[186:189], v[52:55]
	v_mfma_f32_16x16x32_bf16 v[48:51], v[178:181], v[186:189], v[48:51]
	v_mfma_f32_16x16x32_bf16 v[36:39], v[170:173], v[194:197], v[36:39]
	v_mfma_f32_16x16x32_bf16 v[32:35], v[178:181], v[194:197], v[32:35]
	v_mfma_f32_16x16x32_bf16 v[20:23], v[170:173], v[202:205], v[20:23]
	v_mfma_f32_16x16x32_bf16 v[16:19], v[178:181], v[202:205], v[16:19]
	v_mfma_f32_16x16x32_bf16 v[4:7], v[170:173], v[210:213], v[4:7]
	v_mfma_f32_16x16x32_bf16 v[0:3], v[178:181], v[210:213], v[0:3]
	s_setprio 0
	s_barrier
	s_cmp_eq_u32 s73, 4
	s_cselect_b32 s78, s77, 0
	s_sub_u32 s71, s71, s78
	s_subb_u32 s72, s72, 0
	s_sub_u32 s4, s4, s78
	s_subb_u32 s5, s5, 0
	s_add_i32 s73, s73, 2
	s_add_u32 s71, s71, 0x100
	s_addc_u32 s72, s72, 0
	s_add_u32 s4, s4, 0x100
	s_addc_u32 s5, s5, 0
	s_cmp_gt_u32 s73, 13
	s_cbranch_scc0 .LBB0_166
	s_and_b64 vcc, exec, s[16:17]
	s_cbranch_vccz .LBB0_169
	s_barrier

; __device__ __forceinline__ bool tile_of(long L, int nM, int nN, int& pm, int& pn) {
;     const int nwg = nM * nN; if (L >= nwg) return false;
;     int wgid = (int)L; { const int q = nwg / NXCD, r = nwg % NXCD, xcd = wgid % NXCD, off = wgid / NXCD; wgid = (xcd < r ? xcd * (q + 1) : r * (q + 1) + (xcd - r) * q) + off; }
;     const int nig = WGM * nN, gid = wgid / nig, fm = gid * WGM, gsz = (nM - fm) < WGM ? (nM - fm) : WGM;
;     pm = fm + ((wgid % nig) % gsz); pn = (wgid % nig) / gsz; return true;
; }
;     __device__ __forceinline__ bool next(int i, Unit& u) const {
;         int pm, pn; if (!tile_of((long)i * G + c, nM, nN, pm, pn)) return false;
;         u.a = A + (size_t)pm * BM * lda * 2; u.b = Bt + (size_t)pn * BM * ldb * 2; u.row0 = pm * BM; u.col0 = col_base + pn * BM; u.vlo = 0; u.vhi = 0x7fffffff; u.aux = pn; return true;
;     }
.LBB0_1387:
	s_add_i32 s28, s28, 1
	s_mul_i32 s4, s28, s68
	s_mul_hi_u32 s5, s28, s40
	s_add_i32 s5, s5, s4
	s_mul_i32 s4, s28, s40
	s_add_u32 s6, s4, s41
	s_addc_u32 s7, s5, s69
	v_mov_b64_e32 v[0:1], 0x16b0
	v_cmp_lt_i64_e64 s[4:5], s[6:7], v[0:1]
	v_mov_b64_e32 v[0:1], 0x16af
	v_cmp_gt_i64_e32 vcc, s[6:7], v[0:1]
	s_cbranch_vccnz .LBB0_1389
	s_ashr_i32 s7, s6, 31
	s_lshr_b32 s7, s7, 29
	s_add_i32 s7, s6, s7
	s_ashr_i32 s14, s7, 3
	s_and_b32 s7, s7, -8
	s_sub_i32 s6, s6, s7
	s_cmp_lt_i32 s6, 0
	s_movk_i32 s7, 0x2d7
	s_cselect_b32 s7, s7, 0x2d6
	s_mul_i32 s6, s7, s6
	s_add_i32 s6, s6, s14
	s_mul_hi_i32 s7, s6, 0x2e8ba2e9
	s_lshr_b32 s14, s7, 31
	s_ashr_i32 s7, s7, 5
	s_add_i32 s7, s7, s14
	s_lshl_b32 s14, s7, 3
	s_sub_i32 s15, 0x108, s14
	s_min_i32 s15, s15, 8
	s_abs_i32 s38, s15
	v_cvt_f32_u32_e32 v0, s38
	s_sub_i32 s48, 0, s38
	s_mulk_i32 s7, 0xb0
	s_sub_i32 s7, s6, s7
	v_rcp_iflag_f32_e32 v0, v0
	s_abs_i32 s6, s7
	s_xor_b32 s39, s7, s15
	s_ashr_i32 s39, s39, 31
	v_mul_f32_e32 v0, 0x4f7ffffe, v0
	v_cvt_u32_f32_e32 v0, v0
	s_nop 0
	v_readfirstlane_b32 s49, v0
	s_mul_i32 s48, s48, s49
	s_mul_hi_u32 s48, s49, s48
	s_add_i32 s49, s49, s48
	s_mul_hi_u32 s48, s6, s49
	s_mul_i32 s49, s48, s38
	s_sub_i32 s6, s6, s49
	s_add_i32 s56, s48, 1
	s_sub_i32 s49, s6, s38
	s_cmp_ge_u32 s6, s38
	s_cselect_b32 s48, s56, s48
	s_cselect_b32 s6, s49, s6
	s_add_i32 s49, s48, 1
	s_cmp_ge_u32 s6, s38
	s_cselect_b32 s6, s49, s48
	s_xor_b32 s6, s6, s39
	s_sub_i32 s6, s6, s39
	s_mul_i32 s15, s6, s15
	s_sub_i32 s7, s7, s15
	s_add_i32 s14, s7, s14
	s_ashr_i32 s15, s14, 31
	s_lshl_b64 s[38:39], s[14:15], 19
	s_add_u32 s94, s42, s38
	s_addc_u32 s95, s43, s39
	s_ashr_i32 s7, s6, 31
	s_lshl_b64 s[38:39], s[6:7], 19
	s_add_u32 s96, s50, s38
	s_addc_u32 s97, s51, s39
	s_bitcmp1_b32 s28, 0
	s_cselect_b32 s32, 0x400, 0
	s_add_u32 s94, s94, s32
	s_addc_u32 s95, s95, 0
	s_add_u32 s96, s96, s32
	s_addc_u32 s97, s97, 0
	s_lshl_b32 s61, s14, 8
	s_lshl_b32 s60, s6, 8
.LBB0_1389:
	s_bitcmp0_b32 s28, 0
	s_cselect_b32 s57, 0x800, 0
	s_add_u32 s14, s12, 0x100
	s_addc_u32 s15, s13, 0
	s_add_u32 s6, s10, 0x40080
	v_mov_b32_e32 v96, 0
	s_addc_u32 s7, s11, 0
	s_mov_b32 s38, -2
	v_mov_b32_e32 v97, v96
	v_mov_b32_e32 v98, v96
	v_mov_b32_e32 v99, v96
	v_mov_b32_e32 v100, v96
	v_mov_b32_e32 v101, v96
	v_mov_b32_e32 v102, v96
	v_mov_b32_e32 v103, v96
	v_mov_b32_e32 v0, v96
	v_mov_b32_e32 v1, v96
	v_mov_b32_e32 v2, v96
	v_mov_b32_e32 v3, v96
	v_mov_b32_e32 v4, v96
	v_mov_b32_e32 v5, v96
	v_mov_b32_e32 v6, v96
	v_mov_b32_e32 v7, v96
	v_mov_b32_e32 v16, v96
	v_mov_b32_e32 v17, v96
	v_mov_b32_e32 v18, v96
	v_mov_b32_e32 v19, v96
	v_mov_b32_e32 v20, v96
	v_mov_b32_e32 v21, v96
	v_mov_b32_e32 v22, v96
	v_mov_b32_e32 v23, v96
	v_mov_b32_e32 v32, v96
	v_mov_b32_e32 v33, v96
	v_mov_b32_e32 v34, v96
	v_mov_b32_e32 v35, v96
	v_mov_b32_e32 v36, v96
	v_mov_b32_e32 v37, v96
	v_mov_b32_e32 v38, v96
	v_mov_b32_e32 v39, v96
	v_mov_b32_e32 v104, v96
	v_mov_b32_e32 v105, v96
	v_mov_b32_e32 v106, v96
	v_mov_b32_e32 v107, v96
	v_mov_b32_e32 v108, v96
	v_mov_b32_e32 v109, v96
	v_mov_b32_e32 v110, v96
	v_mov_b32_e32 v111, v96
	v_mov_b32_e32 v8, v96
	v_mov_b32_e32 v9, v96
	v_mov_b32_e32 v10, v96
	v_mov_b32_e32 v11, v96
	v_mov_b32_e32 v12, v96
	v_mov_b32_e32 v13, v96
	v_mov_b32_e32 v14, v96
	v_mov_b32_e32 v15, v96
	v_mov_b32_e32 v24, v96
	v_mov_b32_e32 v25, v96
	v_mov_b32_e32 v26, v96
	v_mov_b32_e32 v27, v96
	v_mov_b32_e32 v28, v96
	v_mov_b32_e32 v29, v96
	v_mov_b32_e32 v30, v96
	v_mov_b32_e32 v31, v96
	v_mov_b32_e32 v40, v96
	v_mov_b32_e32 v41, v96
	v_mov_b32_e32 v42, v96
	v_mov_b32_e32 v43, v96
	v_mov_b32_e32 v44, v96
	v_mov_b32_e32 v45, v96
	v_mov_b32_e32 v46, v96
	v_mov_b32_e32 v47, v96
	v_mov_b32_e32 v112, v96
	v_mov_b32_e32 v113, v96
	v_mov_b32_e32 v114, v96
	v_mov_b32_e32 v115, v96
	v_mov_b32_e32 v116, v96
	v_mov_b32_e32 v117, v96
	v_mov_b32_e32 v118, v96
	v_mov_b32_e32 v119, v96
	v_mov_b32_e32 v48, v96
	v_mov_b32_e32 v49, v96
	v_mov_b32_e32 v50, v96
	v_mov_b32_e32 v51, v96
	v_mov_b32_e32 v52, v96
	v_mov_b32_e32 v53, v96
	v_mov_b32_e32 v54, v96
	v_mov_b32_e32 v55, v96
	v_mov_b32_e32 v64, v96
	v_mov_b32_e32 v65, v96
	v_mov_b32_e32 v66, v96
	v_mov_b32_e32 v67, v96
	v_mov_b32_e32 v68, v96
	v_mov_b32_e32 v69, v96
	v_mov_b32_e32 v70, v96
	v_mov_b32_e32 v71, v96
	v_mov_b32_e32 v80, v96
	v_mov_b32_e32 v81, v96
	v_mov_b32_e32 v82, v96
	v_mov_b32_e32 v83, v96
	v_mov_b32_e32 v84, v96
	v_mov_b32_e32 v85, v96
	v_mov_b32_e32 v86, v96
	v_mov_b32_e32 v87, v96
	v_mov_b32_e32 v120, v96
	v_mov_b32_e32 v121, v96
	v_mov_b32_e32 v122, v96
	v_mov_b32_e32 v123, v96
	v_mov_b32_e32 v124, v96
	v_mov_b32_e32 v125, v96
	v_mov_b32_e32 v126, v96
	v_mov_b32_e32 v127, v96
	v_mov_b32_e32 v56, v96
	v_mov_b32_e32 v57, v96
	v_mov_b32_e32 v58, v96
	v_mov_b32_e32 v59, v96
	v_mov_b32_e32 v60, v96
	v_mov_b32_e32 v61, v96
	v_mov_b32_e32 v62, v96
	v_mov_b32_e32 v63, v96
	v_mov_b32_e32 v72, v96
	v_mov_b32_e32 v73, v96
	v_mov_b32_e32 v74, v96
	v_mov_b32_e32 v75, v96
	v_mov_b32_e32 v76, v96
	v_mov_b32_e32 v77, v96
	v_mov_b32_e32 v78, v96
	v_mov_b32_e32 v79, v96
	v_mov_b32_e32 v88, v96
	v_mov_b32_e32 v89, v96
	v_mov_b32_e32 v90, v96
	v_mov_b32_e32 v91, v96
	v_mov_b32_e32 v92, v96
	v_mov_b32_e32 v93, v96
	v_mov_b32_e32 v94, v96
	v_mov_b32_e32 v95, v96
; #define PG8_STAGE(bufoff, gbase, voff) do { _Pragma("unroll") for (int _i = 0; _i < 2; ++_i) \
;         __builtin_amdgcn_global_load_lds((const unsigned*)((const char*)(gbase) + (voff)[_i]), (LAS unsigned*)(lds + (bufoff) + ldsw + _i * 8192), 16, 0, 0); } while (0)
; #define PG8_LDA(dst, b, h) do { _Pragma("unroll") for (int m = 0; m < 4; ++m) _Pragma("unroll") for (int k = 0; k < 2; ++k) dst[m][k] = *(const LAS bf16x8*)(lds + PG8_SA(b, h) + aoff + m * 2048 + k * 1024); } while (0)
; #define PG8_LDB(dst, b, h) do { _Pragma("unroll") for (int n = 0; n < 2; ++n) _Pragma("unroll") for (int k = 0; k < 2; ++k) dst[n][k] = *(const LAS bf16x8*)(lds + PG8_SB(b, h) + boff + n * 2048 + k * 1024); } while (0)
; #define PG8_MMA(ai, bj, At, Bt) do { __builtin_amdgcn_s_setprio(1); _Pragma("unroll") for (int m = 0; m < 4; ++m) _Pragma("unroll") for (int n = 0; n < 2; ++n) _Pragma("unroll") for (int k = 0; k < 2; ++k) \
;         acc[ai][bj][m][n] = __builtin_amdgcn_mfma_f32_16x16x32_bf16(Bt[n][k], At[m][k], acc[ai][bj][m][n], 0, 0, 0); __builtin_amdgcn_s_setprio(0); } while (0)
; #define PG8_WAIT_V(n) asm volatile("s_waitcnt vmcnt(" #n ")" ::: "memory")
; #define PG8_WAIT_L(n) asm volatile("s_waitcnt lgkmcnt(" #n ")" ::: "memory")
; #define PG8_BAR __builtin_amdgcn_s_barrier()
; #define PG8_SCHED __builtin_amdgcn_sched_barrier(0)
; template <class Epi, class Sched>
; __device__ __forceinline__ void gemm_phase(LAS unsigned char* lds, const GemmP g, const Sched& S, const Epi& E, int tid) {
;     ...
;         for (int t = 0; t < nt; t += 2) {
;             const bool last = (t == nt - 2);
;             const char* a1 = cA + (size_t)(t + 1) * kstep;
;             const char* a2 = last ? nA : cA + (size_t)(t + 2) * kstep; const char* b2 = last ? nB : cB + (size_t)(t + 2) * kstep;
;             const char* a3 = a2 + kstep; const char* b3 = b2 + kstep;
;             PG8_LDB(B0, 0, 0); PG8_LDB(B1, 0, 1); PG8_SCHED; PG8_LDA(At, 0, 0); PG8_STAGE(PG8_SA(1, 1), a1 + hstepA, voffA);
;             PG8_WAIT_V(8); PG8_WAIT_L(0); PG8_BAR; PG8_MMA(0, 0, At, B0); PG8_MMA(0, 1, At, B1); PG8_BAR; PG8_SCHED;
;             PG8_LDA(At, 0, 1); PG8_STAGE(PG8_SB(0, 0), b2, voffB); PG8_STAGE(PG8_SB(0, 1), b2 + hstepB, voffB); PG8_STAGE(PG8_SA(0, 0), a2, voffA);
;             PG8_WAIT_V(8); PG8_WAIT_L(0); PG8_BAR; PG8_MMA(1, 0, At, B0); PG8_MMA(1, 1, At, B1); PG8_BAR; PG8_SCHED;
.LBB0_1390:
	s_add_u32 s10, s6, 0xfffc0080
	s_addc_u32 s11, s7, -1
	s_add_i32 s39, 0, 0x10000
	s_cmp_eq_u32 s38, 12
	s_cselect_b32 s13, s95, s11
	s_cselect_b32 s12, s94, s10
	v_add_u32_e32 v144, s39, v146
	s_cselect_b32 s11, s97, s15
	s_cselect_b32 s10, s96, s14
	s_cmp_eq_u32 s38, 4
	s_cselect_b32 s32, s57, 0
	s_sub_u32 s10, s10, s32
	s_subb_u32 s11, s11, 0
	s_sub_u32 s12, s12, s32
	s_subb_u32 s13, s13, 0
	s_add_i32 s56, 0, 0x14000
	ds_read_b128 v[140:143], v144
	ds_read_b128 v[148:151], v144 offset:1024
	ds_read_b128 v[152:155], v144 offset:2048
	ds_read_b128 v[156:159], v144 offset:3072
	v_add_u32_e32 v144, s56, v146
	ds_read_b128 v[160:163], v144
	ds_read_b128 v[164:167], v144 offset:1024
	ds_read_b128 v[168:171], v144 offset:2048
	ds_read_b128 v[172:175], v144 offset:3072
	v_lshl_add_u64 v[144:145], s[6:7], 0, v[138:139]
	s_add_i32 m0, s53, 0xc000
	ds_read_b128 v[176:179], v147
	ds_read_b128 v[180:183], v147 offset:1024
	ds_read_b128 v[184:187], v147 offset:2048
	ds_read_b128 v[188:191], v147 offset:3072
	ds_read_b128 v[192:195], v147 offset:4096
	ds_read_b128 v[206:209], v147 offset:5120
	ds_read_b128 v[210:213], v147 offset:6144
	ds_read_b128 v[214:217], v147 offset:7168
	global_load_lds_dwordx4 v[144:145], off
	v_lshl_add_u64 v[144:145], s[6:7], 0, v[136:137]
	s_add_i32 m0, s53, 0xe000
	s_nop 0
	global_load_lds_dwordx4 v[144:145], off
	s_cmp_eq_u32 s38, -2
	s_cbranch_scc1 .Lfirstit_5
	s_waitcnt vmcnt(8)
.Lfirstit_5:
	s_waitcnt lgkmcnt(0)
	s_barrier
	s_setprio 1
	s_waitcnt lgkmcnt(0)
	v_mfma_f32_16x16x32_bf16 v[92:95], v[140:143], v[176:179], v[92:95]
	v_mfma_f32_16x16x32_bf16 v[88:91], v[152:155], v[176:179], v[88:91]
	v_mfma_f32_16x16x32_bf16 v[76:79], v[140:143], v[184:187], v[76:79]
	v_mfma_f32_16x16x32_bf16 v[72:75], v[152:155], v[184:187], v[72:75]
	v_mfma_f32_16x16x32_bf16 v[60:63], v[140:143], v[192:195], v[60:63]
	v_mfma_f32_16x16x32_bf16 v[56:59], v[152:155], v[192:195], v[56:59]
	v_mfma_f32_16x16x32_bf16 v[124:127], v[140:143], v[210:213], v[124:127]
	v_mfma_f32_16x16x32_bf16 v[120:123], v[152:155], v[210:213], v[120:123]
	v_mfma_f32_16x16x32_bf16 v[92:95], v[148:151], v[180:183], v[92:95]
	v_mfma_f32_16x16x32_bf16 v[88:91], v[156:159], v[180:183], v[88:91]
	v_mfma_f32_16x16x32_bf16 v[76:79], v[148:151], v[188:191], v[76:79]
	v_mfma_f32_16x16x32_bf16 v[72:75], v[156:159], v[188:191], v[72:75]
	v_mfma_f32_16x16x32_bf16 v[60:63], v[148:151], v[206:209], v[60:63]
	v_mfma_f32_16x16x32_bf16 v[56:59], v[156:159], v[206:209], v[56:59]
	v_mfma_f32_16x16x32_bf16 v[124:127], v[148:151], v[214:217], v[124:127]
	v_mfma_f32_16x16x32_bf16 v[120:123], v[156:159], v[214:217], v[120:123]
	s_setprio 0
	s_setprio 1
	v_mfma_f32_16x16x32_bf16 v[84:87], v[160:163], v[176:179], v[84:87]
	v_mfma_f32_16x16x32_bf16 v[80:83], v[168:171], v[176:179], v[80:83]
	v_mfma_f32_16x16x32_bf16 v[68:71], v[160:163], v[184:187], v[68:71]
	v_mfma_f32_16x16x32_bf16 v[64:67], v[168:171], v[184:187], v[64:67]
	v_mfma_f32_16x16x32_bf16 v[52:55], v[160:163], v[192:195], v[52:55]
	v_mfma_f32_16x16x32_bf16 v[48:51], v[168:171], v[192:195], v[48:51]
	v_mfma_f32_16x16x32_bf16 v[116:119], v[160:163], v[210:213], v[116:119]
	v_mfma_f32_16x16x32_bf16 v[112:115], v[168:171], v[210:213], v[112:115]
	v_mfma_f32_16x16x32_bf16 v[84:87], v[164:167], v[180:183], v[84:87]
	v_mfma_f32_16x16x32_bf16 v[80:83], v[172:175], v[180:183], v[80:83]
	v_mfma_f32_16x16x32_bf16 v[68:71], v[164:167], v[188:191], v[68:71]
	v_mfma_f32_16x16x32_bf16 v[64:67], v[172:175], v[188:191], v[64:67]
	v_mfma_f32_16x16x32_bf16 v[52:55], v[164:167], v[206:209], v[52:55]
	v_mfma_f32_16x16x32_bf16 v[48:51], v[172:175], v[206:209], v[48:51]
	v_mfma_f32_16x16x32_bf16 v[116:119], v[164:167], v[214:217], v[116:119]
	v_mfma_f32_16x16x32_bf16 v[112:115], v[172:175], v[214:217], v[112:115]
	s_setprio 0
	s_barrier
	s_add_i32 s39, s39, s52
	v_lshl_add_u64 v[144:145], s[10:11], 0, v[130:131]
	s_mov_b32 m0, s39
	ds_read_b128 v[176:179], v147 offset:16384
	ds_read_b128 v[180:183], v147 offset:17408
	ds_read_b128 v[184:187], v147 offset:18432
	ds_read_b128 v[188:191], v147 offset:19456
	ds_read_b128 v[192:195], v147 offset:20480
	ds_read_b128 v[206:209], v147 offset:21504
	ds_read_b128 v[210:213], v147 offset:22528
	ds_read_b128 v[214:217], v147 offset:23552
	global_load_lds_dwordx4 v[144:145], off
	s_add_i32 m0, s39, 0x2000
	s_add_u32 s48, s10, 0x40000
	v_lshl_add_u64 v[198:199], s[10:11], 0, v[134:135]
	s_addc_u32 s49, s11, 0
	s_add_i32 s39, s56, s52
	global_load_lds_dwordx4 v[198:199], off
	v_lshl_add_u64 v[200:201], s[48:49], 0, v[130:131]
	s_mov_b32 m0, s39
	v_lshl_add_u64 v[220:221], s[12:13], 0, v[132:133]
	global_load_lds_dwordx4 v[200:201], off
	v_lshl_add_u64 v[200:201], s[48:49], 0, v[134:135]
	s_add_i32 m0, s39, 0x2000
	s_nop 0
	global_load_lds_dwordx4 v[200:201], off
	v_lshl_add_u64 v[200:201], s[12:13], 0, v[128:129]
	s_mov_b32 m0, s53
	s_nop 0
	global_load_lds_dwordx4 v[200:201], off
	s_mov_b32 m0, s54
	s_nop 0
	global_load_lds_dwordx4 v[220:221], off
	s_waitcnt vmcnt(8)
	s_waitcnt lgkmcnt(0)
	s_barrier
; #define PG8_STAGE(bufoff, gbase, voff) do { _Pragma("unroll") for (int _i = 0; _i < 2; ++_i) \
;         __builtin_amdgcn_global_load_lds((const unsigned*)((const char*)(gbase) + (voff)[_i]), (LAS unsigned*)(lds + (bufoff) + ldsw + _i * 8192), 16, 0, 0); } while (0)
; #define PG8_LDA(dst, b, h) do { _Pragma("unroll") for (int m = 0; m < 4; ++m) _Pragma("unroll") for (int k = 0; k < 2; ++k) dst[m][k] = *(const LAS bf16x8*)(lds + PG8_SA(b, h) + aoff + m * 2048 + k * 1024); } while (0)
; #define PG8_LDB(dst, b, h) do { _Pragma("unroll") for (int n = 0; n < 2; ++n) _Pragma("unroll") for (int k = 0; k < 2; ++k) dst[n][k] = *(const LAS bf16x8*)(lds + PG8_SB(b, h) + boff + n * 2048 + k * 1024); } while (0)
; #define PG8_MMA(ai, bj, At, Bt) do { __builtin_amdgcn_s_setprio(1); _Pragma("unroll") for (int m = 0; m < 4; ++m) _Pragma("unroll") for (int n = 0; n < 2; ++n) _Pragma("unroll") for (int k = 0; k < 2; ++k) \
;         acc[ai][bj][m][n] = __builtin_amdgcn_mfma_f32_16x16x32_bf16(Bt[n][k], At[m][k], acc[ai][bj][m][n], 0, 0, 0); __builtin_amdgcn_s_setprio(0); } while (0)
; #define PG8_WAIT_V(n) asm volatile("s_waitcnt vmcnt(" #n ")" ::: "memory")
; #define PG8_WAIT_L(n) asm volatile("s_waitcnt lgkmcnt(" #n ")" ::: "memory")
; #define PG8_BAR __builtin_amdgcn_s_barrier()
; #define PG8_SCHED __builtin_amdgcn_sched_barrier(0)
; template <class Epi, class Sched>
; __device__ __forceinline__ void gemm_phase(LAS unsigned char* lds, const GemmP g, const Sched& S, const Epi& E, int tid) {
;     ...
;             PG8_WAIT_V(8); PG8_WAIT_L(0); PG8_BAR; PG8_MMA(1, 0, At, B0); PG8_MMA(1, 1, At, B1); PG8_BAR; PG8_SCHED;
;             PG8_LDB(B0, 1, 0); PG8_LDB(B1, 1, 1); PG8_SCHED; PG8_LDA(At, 1, 0); PG8_STAGE(PG8_SA(0, 1), a2 + hstepA, voffA);
;             PG8_WAIT_V(8); PG8_WAIT_L(0); PG8_BAR; PG8_MMA(0, 0, At, B0); PG8_MMA(0, 1, At, B1); PG8_BAR; PG8_SCHED;
	s_setprio 1
	s_waitcnt lgkmcnt(0)
	v_mfma_f32_16x16x32_bf16 v[44:47], v[140:143], v[176:179], v[44:47]
	v_mfma_f32_16x16x32_bf16 v[40:43], v[152:155], v[176:179], v[40:43]
	v_mfma_f32_16x16x32_bf16 v[28:31], v[140:143], v[184:187], v[28:31]
	v_mfma_f32_16x16x32_bf16 v[24:27], v[152:155], v[184:187], v[24:27]
	v_mfma_f32_16x16x32_bf16 v[12:15], v[140:143], v[192:195], v[12:15]
	v_mfma_f32_16x16x32_bf16 v[8:11], v[152:155], v[192:195], v[8:11]
	v_mfma_f32_16x16x32_bf16 v[108:111], v[140:143], v[210:213], v[108:111]
	v_mfma_f32_16x16x32_bf16 v[104:107], v[152:155], v[210:213], v[104:107]
	v_mfma_f32_16x16x32_bf16 v[44:47], v[148:151], v[180:183], v[44:47]
	v_mfma_f32_16x16x32_bf16 v[40:43], v[156:159], v[180:183], v[40:43]
	v_mfma_f32_16x16x32_bf16 v[28:31], v[148:151], v[188:191], v[28:31]
	v_mfma_f32_16x16x32_bf16 v[24:27], v[156:159], v[188:191], v[24:27]
	v_mfma_f32_16x16x32_bf16 v[12:15], v[148:151], v[206:209], v[12:15]
	v_mfma_f32_16x16x32_bf16 v[8:11], v[156:159], v[206:209], v[8:11]
	v_mfma_f32_16x16x32_bf16 v[108:111], v[148:151], v[214:217], v[108:111]
	v_mfma_f32_16x16x32_bf16 v[104:107], v[156:159], v[214:217], v[104:107]
	s_setprio 0
	s_setprio 1
	v_mfma_f32_16x16x32_bf16 v[36:39], v[160:163], v[176:179], v[36:39]
	v_mfma_f32_16x16x32_bf16 v[32:35], v[168:171], v[176:179], v[32:35]
	v_mfma_f32_16x16x32_bf16 v[20:23], v[160:163], v[184:187], v[20:23]
	v_mfma_f32_16x16x32_bf16 v[16:19], v[168:171], v[184:187], v[16:19]
	v_mfma_f32_16x16x32_bf16 v[4:7], v[160:163], v[192:195], v[4:7]
	v_mfma_f32_16x16x32_bf16 v[0:3], v[168:171], v[192:195], v[0:3]
	v_mfma_f32_16x16x32_bf16 v[100:103], v[160:163], v[210:213], v[100:103]
	v_mfma_f32_16x16x32_bf16 v[96:99], v[168:171], v[210:213], v[96:99]
	v_mfma_f32_16x16x32_bf16 v[36:39], v[164:167], v[180:183], v[36:39]
	v_mfma_f32_16x16x32_bf16 v[32:35], v[172:175], v[180:183], v[32:35]
	v_mfma_f32_16x16x32_bf16 v[20:23], v[164:167], v[188:191], v[20:23]
	v_mfma_f32_16x16x32_bf16 v[16:19], v[172:175], v[188:191], v[16:19]
	v_mfma_f32_16x16x32_bf16 v[4:7], v[164:167], v[206:209], v[4:7]
	v_mfma_f32_16x16x32_bf16 v[0:3], v[172:175], v[206:209], v[0:3]
	v_mfma_f32_16x16x32_bf16 v[100:103], v[164:167], v[214:217], v[100:103]
	v_mfma_f32_16x16x32_bf16 v[96:99], v[172:175], v[214:217], v[96:99]
	s_setprio 0
	s_barrier
	s_add_i32 s39, 0, 0x18000
	s_add_i32 s48, 0, 0x1c000
	v_add_u32_e32 v156, s39, v146
	v_add_u32_e32 v172, s48, v146
	ds_read_b128 v[140:143], v156
	ds_read_b128 v[148:151], v156 offset:1024
	ds_read_b128 v[152:155], v156 offset:2048
	ds_read_b128 v[156:159], v156 offset:3072
	ds_read_b128 v[160:163], v172
	ds_read_b128 v[164:167], v172 offset:1024
	ds_read_b128 v[168:171], v172 offset:2048
	ds_read_b128 v[172:175], v172 offset:3072
	s_add_u32 s12, s12, 0x40000
	s_addc_u32 s13, s13, 0
	s_mov_b32 m0, s58
	v_lshl_add_u64 v[222:223], s[12:13], 0, v[128:129]
	ds_read_b128 v[176:179], v147 offset:32768
	ds_read_b128 v[180:183], v147 offset:33792
	ds_read_b128 v[184:187], v147 offset:34816
	ds_read_b128 v[188:191], v147 offset:35840
	ds_read_b128 v[192:195], v147 offset:36864
	ds_read_b128 v[206:209], v147 offset:37888
	ds_read_b128 v[210:213], v147 offset:38912
	ds_read_b128 v[214:217], v147 offset:39936
	global_load_lds_dwordx4 v[222:223], off
	v_lshl_add_u64 v[222:223], s[12:13], 0, v[132:133]
	s_mov_b32 m0, s59
	s_nop 0
	global_load_lds_dwordx4 v[222:223], off
	s_waitcnt vmcnt(8)
	s_waitcnt lgkmcnt(0)
	s_barrier
	s_setprio 1
	s_waitcnt lgkmcnt(0)
	v_mfma_f32_16x16x32_bf16 v[92:95], v[140:143], v[176:179], v[92:95]
	v_mfma_f32_16x16x32_bf16 v[88:91], v[152:155], v[176:179], v[88:91]
	v_mfma_f32_16x16x32_bf16 v[76:79], v[140:143], v[184:187], v[76:79]
	v_mfma_f32_16x16x32_bf16 v[72:75], v[152:155], v[184:187], v[72:75]
	v_mfma_f32_16x16x32_bf16 v[60:63], v[140:143], v[192:195], v[60:63]
	v_mfma_f32_16x16x32_bf16 v[56:59], v[152:155], v[192:195], v[56:59]
	v_mfma_f32_16x16x32_bf16 v[124:127], v[140:143], v[210:213], v[124:127]
	v_mfma_f32_16x16x32_bf16 v[120:123], v[152:155], v[210:213], v[120:123]
	v_mfma_f32_16x16x32_bf16 v[92:95], v[148:151], v[180:183], v[92:95]
	v_mfma_f32_16x16x32_bf16 v[88:91], v[156:159], v[180:183], v[88:91]
	v_mfma_f32_16x16x32_bf16 v[76:79], v[148:151], v[188:191], v[76:79]
	v_mfma_f32_16x16x32_bf16 v[72:75], v[156:159], v[188:191], v[72:75]
	v_mfma_f32_16x16x32_bf16 v[60:63], v[148:151], v[206:209], v[60:63]
	v_mfma_f32_16x16x32_bf16 v[56:59], v[156:159], v[206:209], v[56:59]
	v_mfma_f32_16x16x32_bf16 v[124:127], v[148:151], v[214:217], v[124:127]
	v_mfma_f32_16x16x32_bf16 v[120:123], v[156:159], v[214:217], v[120:123]
	s_setprio 0
	s_setprio 1
	v_mfma_f32_16x16x32_bf16 v[84:87], v[160:163], v[176:179], v[84:87]
	v_mfma_f32_16x16x32_bf16 v[80:83], v[168:171], v[176:179], v[80:83]
	v_mfma_f32_16x16x32_bf16 v[68:71], v[160:163], v[184:187], v[68:71]
	v_mfma_f32_16x16x32_bf16 v[64:67], v[168:171], v[184:187], v[64:67]
	v_mfma_f32_16x16x32_bf16 v[52:55], v[160:163], v[192:195], v[52:55]
	v_mfma_f32_16x16x32_bf16 v[48:51], v[168:171], v[192:195], v[48:51]
	v_mfma_f32_16x16x32_bf16 v[116:119], v[160:163], v[210:213], v[116:119]
	v_mfma_f32_16x16x32_bf16 v[112:115], v[168:171], v[210:213], v[112:115]
	v_mfma_f32_16x16x32_bf16 v[84:87], v[164:167], v[180:183], v[84:87]
	v_mfma_f32_16x16x32_bf16 v[80:83], v[172:175], v[180:183], v[80:83]
	v_mfma_f32_16x16x32_bf16 v[68:71], v[164:167], v[188:191], v[68:71]
	v_mfma_f32_16x16x32_bf16 v[64:67], v[172:175], v[188:191], v[64:67]
	v_mfma_f32_16x16x32_bf16 v[52:55], v[164:167], v[206:209], v[52:55]
	v_mfma_f32_16x16x32_bf16 v[48:51], v[172:175], v[206:209], v[48:51]
	v_mfma_f32_16x16x32_bf16 v[116:119], v[164:167], v[214:217], v[116:119]
	v_mfma_f32_16x16x32_bf16 v[112:115], v[172:175], v[214:217], v[112:115]
	s_setprio 0
	s_barrier
; #define PG8_STAGE(bufoff, gbase, voff) do { _Pragma("unroll") for (int _i = 0; _i < 2; ++_i) \
;         __builtin_amdgcn_global_load_lds((const unsigned*)((const char*)(gbase) + (voff)[_i]), (LAS unsigned*)(lds + (bufoff) + ldsw + _i * 8192), 16, 0, 0); } while (0)
; #define PG8_LDA(dst, b, h) do { _Pragma("unroll") for (int m = 0; m < 4; ++m) _Pragma("unroll") for (int k = 0; k < 2; ++k) dst[m][k] = *(const LAS bf16x8*)(lds + PG8_SA(b, h) + aoff + m * 2048 + k * 1024); } while (0)
; #define PG8_MMA(ai, bj, At, Bt) do { __builtin_amdgcn_s_setprio(1); _Pragma("unroll") for (int m = 0; m < 4; ++m) _Pragma("unroll") for (int n = 0; n < 2; ++n) _Pragma("unroll") for (int k = 0; k < 2; ++k) \
;         acc[ai][bj][m][n] = __builtin_amdgcn_mfma_f32_16x16x32_bf16(Bt[n][k], At[m][k], acc[ai][bj][m][n], 0, 0, 0); __builtin_amdgcn_s_setprio(0); } while (0)
; #define PG8_WAIT_V(n) asm volatile("s_waitcnt vmcnt(" #n ")" ::: "memory")
; #define PG8_WAIT_L(n) asm volatile("s_waitcnt lgkmcnt(" #n ")" ::: "memory")
; #define PG8_BAR __builtin_amdgcn_s_barrier()
; #define PG8_SCHED __builtin_amdgcn_sched_barrier(0)
; template <class Epi, class Sched>
; __device__ __forceinline__ void gemm_phase(LAS unsigned char* lds, const GemmP g, const Sched& S, const Epi& E, int tid) {
;     ...
;         for (int t = 0; t < nt; t += 2) {
;     ...
;             PG8_LDA(At, 1, 1); PG8_STAGE(PG8_SB(1, 0), b3, voffB); PG8_STAGE(PG8_SB(1, 1), b3 + hstepB, voffB); PG8_STAGE(PG8_SA(1, 0), a3, voffA);
;             PG8_WAIT_V(8); PG8_WAIT_L(0); PG8_BAR; PG8_MMA(1, 0, At, B0); PG8_MMA(1, 1, At, B1); PG8_BAR; PG8_SCHED;
	s_add_i32 s12, s39, s52
	v_lshl_add_u64 v[144:145], v[144:145], 0, s[80:81]
	s_mov_b32 m0, s12
	ds_read_b128 v[176:179], v147 offset:49152
	ds_read_b128 v[180:183], v147 offset:50176
	ds_read_b128 v[184:187], v147 offset:51200
	ds_read_b128 v[188:191], v147 offset:52224
	ds_read_b128 v[192:195], v147 offset:53248
	ds_read_b128 v[206:209], v147 offset:54272
	ds_read_b128 v[210:213], v147 offset:55296
	ds_read_b128 v[214:217], v147 offset:56320
	global_load_lds_dwordx4 v[144:145], off
	s_add_i32 m0, s12, 0x2000
	s_add_u32 s10, s10, 0x40080
	v_lshl_add_u64 v[144:145], v[198:199], 0, s[80:81]
	s_addc_u32 s11, s11, 0
	s_add_i32 s12, s48, s52
	global_load_lds_dwordx4 v[144:145], off
	v_lshl_add_u64 v[144:145], s[10:11], 0, v[130:131]
	s_mov_b32 m0, s12
	s_nop 0
	global_load_lds_dwordx4 v[144:145], off
	v_lshl_add_u64 v[144:145], s[10:11], 0, v[134:135]
	s_add_i32 m0, s12, 0x2000
	s_nop 0
	global_load_lds_dwordx4 v[144:145], off
	v_lshl_add_u64 v[144:145], v[200:201], 0, s[80:81]
	s_mov_b32 m0, s89
	s_nop 0
	global_load_lds_dwordx4 v[144:145], off
	v_lshl_add_u64 v[144:145], v[220:221], 0, s[80:81]
	s_mov_b32 m0, s64
	s_nop 0
	global_load_lds_dwordx4 v[144:145], off
	s_waitcnt vmcnt(8)
	s_waitcnt lgkmcnt(0)
	s_barrier
	s_setprio 1
	s_waitcnt lgkmcnt(0)
	v_mfma_f32_16x16x32_bf16 v[44:47], v[140:143], v[176:179], v[44:47]
	v_mfma_f32_16x16x32_bf16 v[40:43], v[152:155], v[176:179], v[40:43]
	v_mfma_f32_16x16x32_bf16 v[28:31], v[140:143], v[184:187], v[28:31]
	v_mfma_f32_16x16x32_bf16 v[24:27], v[152:155], v[184:187], v[24:27]
	v_mfma_f32_16x16x32_bf16 v[12:15], v[140:143], v[192:195], v[12:15]
	v_mfma_f32_16x16x32_bf16 v[8:11], v[152:155], v[192:195], v[8:11]
	v_mfma_f32_16x16x32_bf16 v[108:111], v[140:143], v[210:213], v[108:111]
	v_mfma_f32_16x16x32_bf16 v[104:107], v[152:155], v[210:213], v[104:107]
	v_mfma_f32_16x16x32_bf16 v[44:47], v[148:151], v[180:183], v[44:47]
	v_mfma_f32_16x16x32_bf16 v[40:43], v[156:159], v[180:183], v[40:43]
	v_mfma_f32_16x16x32_bf16 v[28:31], v[148:151], v[188:191], v[28:31]
	v_mfma_f32_16x16x32_bf16 v[24:27], v[156:159], v[188:191], v[24:27]
	v_mfma_f32_16x16x32_bf16 v[12:15], v[148:151], v[206:209], v[12:15]
	v_mfma_f32_16x16x32_bf16 v[8:11], v[156:159], v[206:209], v[8:11]
	v_mfma_f32_16x16x32_bf16 v[108:111], v[148:151], v[214:217], v[108:111]
	v_mfma_f32_16x16x32_bf16 v[104:107], v[156:159], v[214:217], v[104:107]
	s_setprio 0
	s_setprio 1
	v_mfma_f32_16x16x32_bf16 v[36:39], v[160:163], v[176:179], v[36:39]
	v_mfma_f32_16x16x32_bf16 v[32:35], v[168:171], v[176:179], v[32:35]
	v_mfma_f32_16x16x32_bf16 v[20:23], v[160:163], v[184:187], v[20:23]
	v_mfma_f32_16x16x32_bf16 v[16:19], v[168:171], v[184:187], v[16:19]
	v_mfma_f32_16x16x32_bf16 v[4:7], v[160:163], v[192:195], v[4:7]
	v_mfma_f32_16x16x32_bf16 v[0:3], v[168:171], v[192:195], v[0:3]
	v_mfma_f32_16x16x32_bf16 v[100:103], v[160:163], v[210:213], v[100:103]
	v_mfma_f32_16x16x32_bf16 v[96:99], v[168:171], v[210:213], v[96:99]
	v_mfma_f32_16x16x32_bf16 v[36:39], v[164:167], v[180:183], v[36:39]
	v_mfma_f32_16x16x32_bf16 v[32:35], v[172:175], v[180:183], v[32:35]
	v_mfma_f32_16x16x32_bf16 v[20:23], v[164:167], v[188:191], v[20:23]
	v_mfma_f32_16x16x32_bf16 v[16:19], v[172:175], v[188:191], v[16:19]
	v_mfma_f32_16x16x32_bf16 v[4:7], v[164:167], v[206:209], v[4:7]
	v_mfma_f32_16x16x32_bf16 v[0:3], v[172:175], v[206:209], v[0:3]
	v_mfma_f32_16x16x32_bf16 v[100:103], v[164:167], v[214:217], v[100:103]
	v_mfma_f32_16x16x32_bf16 v[96:99], v[172:175], v[214:217], v[96:99]
	s_setprio 0
	s_barrier
	s_cmp_eq_u32 s38, 4
	s_cselect_b32 s32, s57, 0
	s_sub_u32 s14, s14, s32
	s_subb_u32 s15, s15, 0
	s_sub_u32 s6, s6, s32
	s_subb_u32 s7, s7, 0
	s_add_i32 s38, s38, 2
	s_add_u32 s14, s14, 0x100
	s_addc_u32 s15, s15, 0
	s_add_u32 s6, s6, 0x100
	s_addc_u32 s7, s7, 0
	s_cmp_gt_u32 s38, 13
	s_cbranch_scc0 .LBB0_1390
	s_and_b64 vcc, exec, s[2:3]
	s_cbranch_vccz .LBB0_1393
	s_barrier
